# idle-slot deferral layout 3: all 8 FFN weight transposes + cache_ckv j=1 conversion out of the prologue, ~200 MB per idle slot (W1 exit, FFN-up 9th round, WinA exit)
# speedup vs baseline: 1.0222x; 1.0042x over previous
.LBB0_35:
	s_or_b64 exec, exec, s[4:5]
	s_lshl_b32 s4, s14, 14
	s_add_i32 s4, s4, 0
	s_add_u32 s19, s16, 0x76b32000
	s_addc_u32 s23, s17, 0
	s_add_u32 s25, s16, 0x6eb32000
	s_addc_u32 s40, s17, 0
	s_add_u32 s41, s16, 0x6ab32000
	s_addc_u32 s42, s17, 0
	s_add_u32 s43, s16, 0x6bb32000
	s_addc_u32 s44, s17, 0
	s_add_u32 s13, s16, 0x69332000
	s_addc_u32 s15, s17, 0
	s_add_u32 s45, s16, 0x68732000
	s_addc_u32 s47, s17, 0
	s_add_u32 s48, s16, 0x68132000
	s_addc_u32 s49, s17, 0
	s_add_u32 s50, s16, 0x67732000
	s_addc_u32 s51, s17, 0
	v_lshrrev_b32_e32 v40, 3, v1
	s_add_u32 s52, s16, 0x69b32000
	v_mul_u32_u24_e32 v5, 0x420, v10
	v_lshlrev_b32_e32 v6, 2, v40
	s_addc_u32 s53, s17, 0
	v_lshl_add_u32 v3, v10, 4, s4
	v_add3_u32 v51, s4, v5, v6
	s_lshl_b32 s54, s46, 10
	s_lshl_b32 s4, s14, 7
	s_add_i32 s54, s54, s4
	s_lshl_b32 s4, s14, 6
	v_lshlrev_b32_e32 v34, 2, v1
	s_add_i32 s56, s56, s4
	s_lshl_b32 s4, s46, 8
	s_lshl_b32 s5, s14, 5
	v_and_b32_e32 v2, 28, v34
	v_mov_b32_e32 v43, 0
	v_mul_u32_u24_e32 v4, 0x84, v40
	v_or_b32_e32 v35, 8, v40
	v_or_b32_e32 v49, 16, v40
	v_or_b32_e32 v50, 24, v40
	v_lshlrev_b32_e32 v52, 1, v40
	v_mov_b32_e32 v5, 0x800
	s_add_i32 s57, s4, s5
	s_mov_b32 s7, 0
	v_or_b32_e32 v53, 0x800, v52
	v_lshl_or_b32 v54, v35, 1, v5
	v_lshl_or_b32 v55, v49, 1, v5
	v_lshl_or_b32 v56, v50, 1, v5
	v_mov_b32_e32 v41, v43
	s_lshl_b32 s55, s58, 10
	s_addk_i32 s57, 0xfe00
	s_lshl_b32 s58, s58, 8
	v_lshlrev_b32_e32 v42, 2, v2
	s_movk_i32 s59, 0x1000
	s_movk_i32 s60, 0x7ff
	s_mov_b32 s61, 0x2aaaaaab
	s_movk_i32 s62, 0xc0
	s_movk_i32 s63, 0x7f
	s_movk_i32 s64, 0xff40
	s_movk_i32 s65, 0x1ff
	v_add_u32_e32 v57, v3, v4
	s_mov_b32 s66, 8
	s_branch .LBB0_37

.LBB0_975:
	s_waitcnt vmcnt(0)
	v_readlane_b32 s54, v255, 36
	v_readlane_b32 s55, v255, 37
	s_barrier
	s_mov_b64 s[98:99], exec
	s_mov_b64 exec, -1
	v_readlane_b32 s2, v254, 0
	v_readlane_b32 s3, v255, 24
	s_load_dword s4, s[86:87], 0xc0
	s_waitcnt lgkmcnt(0)
	s_cmp_eq_u32 s3, 0
	s_cbranch_scc0 .Ldl8_sel0
	s_mov_b32 s69, 0
	s_mov_b32 s79, 1
	s_branch .Ldl8_go

.Ldl8_done:
	s_mov_b64 exec, s[98:99]
	s_mov_b64 s[98:99], exec
	s_mov_b64 exec, -1
	v_readlane_b32 s2, v254, 0
	v_readlane_b32 s3, v255, 24
	s_load_dword s4, s[86:87], 0xc0
	s_waitcnt lgkmcnt(0)
	s_cmp_eq_u32 s3, 0
	s_cbranch_scc0 .Ldl7_sel0
	s_mov_b32 s69, 0
	s_mov_b32 s79, 1
	s_branch .Ldl7_go

.Ldl7_done:
	s_mov_b64 exec, s[98:99]
	s_mov_b64 s[98:99], exec
	s_mov_b64 exec, -1
	v_readlane_b32 s2, v254, 0
	v_readlane_b32 s3, v255, 24
	s_load_dword s4, s[86:87], 0xc0
	s_load_dwordx2 s[6:7], s[86:87], 0x10
	s_load_dwordx2 s[88:89], s[86:87], 0xb0
	s_waitcnt lgkmcnt(0)
	s_cmp_eq_u32 s3, 2
	s_cbranch_scc0 .Ldlc_sel0
	s_mov_b32 s91, 0x30000
	s_mov_b32 s79, 0x40000
	s_branch .Ldlc_go

.Ldlc_go:
	s_cmp_eq_u32 s4, 0x100
	s_cbranch_scc0 .Ldlc_all
	s_cmp_lt_u32 s2, 84
	s_cbranch_scc1 .Ldlc_done
	s_sub_u32 s2, s2, 84
	s_movk_i32 s4, 172
.Ldlc_all:
	v_readfirstlane_b32 s5, v0
	s_lshr_b32 s5, s5, 6
	s_lshl_b32 s2, s2, 3
	s_add_u32 s2, s2, s5
	s_lshl_b32 s92, s4, 3
	s_add_u32 s91, s91, s2
	s_add_u32 s88, s88, 0x27b32000
	s_addc_u32 s89, s89, 0
	v_mbcnt_lo_u32_b32 v41, -1, 0
	v_mbcnt_hi_u32_b32 v41, -1, v41
	v_lshlrev_b32_e32 v42, 5, v41
	v_lshlrev_b32_e32 v43, 4, v41
	s_cmp_ge_u32 s91, s79
	s_cbranch_scc1 .Ldlc_done

.LBB0_1964:
	s_waitcnt vmcnt(0)
	v_readlane_b32 s86, v255, 26
	v_readlane_b32 s87, v255, 27
	s_barrier
	s_mov_b64 s[98:99], exec
	s_mov_b64 exec, -1
	v_readlane_b32 s2, v254, 0
	v_readlane_b32 s3, v255, 24
	s_load_dword s4, s[86:87], 0xc0
	s_waitcnt lgkmcnt(0)
	s_cmp_eq_u32 s3, 0
	s_cbranch_scc0 .Ldj8_sel0
	s_mov_b32 s69, 1
	s_mov_b32 s79, 2
	s_branch .Ldj8_go

.Ldj8_go:
	s_cmp_eq_u32 s4, 0x100
	s_cbranch_scc0 .Ldj8_all
	s_cmp_lt_u32 s2, 128
	s_cbranch_scc1 .Ldj8_done
	s_sub_u32 s2, s2, 128
	s_movk_i32 s4, 128
.Ldj8_all:
	v_readfirstlane_b32 s5, v0
	s_lshr_b32 s5, s5, 6
	s_lshl_b32 s2, s2, 3
	s_add_u32 s2, s2, s5
	s_lshl_b32 s92, s4, 3
	v_mbcnt_lo_u32_b32 v41, -1, 0
	v_mbcnt_hi_u32_b32 v41, -1, v41
	v_lshrrev_b32_e32 v42, 3, v41
	v_and_b32_e32 v43, 7, v41
	v_lshlrev_b32_e32 v44, 13, v42
	v_lshl_add_u32 v44, v43, 4, v44
	v_add_u32_e32 v45, 0x10000, v44
	v_add_u32_e32 v46, 0x20000, v44
	v_add_u32_e32 v47, 0x30000, v44
	v_add_u32_e32 v48, 0x40000, v44
	v_add_u32_e32 v49, 0x50000, v44
	v_add_u32_e32 v50, 0x60000, v44
	v_add_u32_e32 v51, 0x70000, v44
	s_lshl_b32 s49, s5, 14
	v_mul_u32_u24_e32 v52, 0x84, v42
	v_lshl_add_u32 v52, v43, 4, v52
	v_add_u32_e32 v52, s49, v52
	v_mul_u32_u24_e32 v53, 0x420, v43
	v_lshl_add_u32 v53, v42, 2, v53
	v_add_u32_e32 v53, s49, v53
	v_lshlrev_b32_e32 v54, 14, v42
	v_lshl_add_u32 v54, v43, 4, v54
	v_add_u32_e32 v55, 0x20000, v54
	v_add_u32_e32 v56, 0x40000, v54
	v_add_u32_e32 v57, 0x60000, v54

.Ldj7_go:
	s_cmp_eq_u32 s4, 0x100
	s_cbranch_scc0 .Ldj7_all
	s_cmp_lt_u32 s2, 128
	s_cbranch_scc1 .Ldj7_done
	s_sub_u32 s2, s2, 128
	s_movk_i32 s4, 128
.Ldj7_all:
	v_readfirstlane_b32 s5, v0
	s_lshr_b32 s5, s5, 6
	s_lshl_b32 s2, s2, 3
	s_add_u32 s2, s2, s5
	s_lshl_b32 s92, s4, 3
	v_mbcnt_lo_u32_b32 v41, -1, 0
	v_mbcnt_hi_u32_b32 v41, -1, v41
	v_lshrrev_b32_e32 v42, 3, v41
	v_and_b32_e32 v43, 7, v41
	v_lshlrev_b32_e32 v44, 15, v42
	v_lshl_add_u32 v44, v43, 4, v44
	v_add_u32_e32 v45, 0x40000, v44
	v_add_u32_e32 v46, 0x80000, v44
	v_add_u32_e32 v47, 0xc0000, v44
	v_add_u32_e32 v48, 0x100000, v44
	v_add_u32_e32 v49, 0x140000, v44
	v_add_u32_e32 v50, 0x180000, v44
	v_add_u32_e32 v51, 0x1c0000, v44
	s_lshl_b32 s49, s5, 14
	v_mul_u32_u24_e32 v52, 0x84, v42
	v_lshl_add_u32 v52, v43, 4, v52
	v_add_u32_e32 v52, s49, v52
	v_mul_u32_u24_e32 v53, 0x420, v43
	v_lshl_add_u32 v53, v42, 2, v53
	v_add_u32_e32 v53, s49, v53
	v_lshlrev_b32_e32 v54, 12, v42
	v_lshl_add_u32 v54, v43, 4, v54
	v_add_u32_e32 v55, 0x8000, v54
	v_add_u32_e32 v56, 0x10000, v54
	v_add_u32_e32 v57, 0x18000, v54
	v_lshlrev_b32_e32 v204, 2, v42

.Ldj7_done:
	s_mov_b64 exec, s[98:99]
	s_mov_b64 s[98:99], exec
	s_mov_b64 exec, -1
	v_readlane_b32 s2, v254, 0
	v_readlane_b32 s3, v255, 24
	s_load_dword s4, s[86:87], 0xc0
	s_load_dwordx2 s[6:7], s[86:87], 0x10
	s_load_dwordx2 s[88:89], s[86:87], 0xb0
	s_waitcnt lgkmcnt(0)
	s_cmp_eq_u32 s3, 1
	s_cbranch_scc0 .Ldck_sel0
	s_mov_b32 s91, 0x20000
	s_mov_b32 s79, 0x30000
	s_branch .Ldck_go
